# plus: top-k mask select in sparse attention via v_bfe_i32+v_bfi_b32 instead of and/cmp/cndmask (45 sites), redundant nops removed
# baseline (speedup 1.0000x reference)
; DI float softmax_step(f32x4 (&st)[4], float& m, float& lsum) {
;   float mx = fmaxf(fmaxf(fmaxf(st[0][0], st[0][1]), fmaxf(st[0][2], st[0][3])), fmaxf(fmaxf(st[1][0], st[1][1]), fmaxf(st[1][2], st[1][3])));
;   mx = fmaxf(mx, fmaxf(fmaxf(fmaxf(st[2][0], st[2][1]), fmaxf(st[2][2], st[2][3])), fmaxf(fmaxf(st[3][0], st[3][1]), fmaxf(st[3][2], st[3][3]))));
;   mx = fmaxf(mx, __shfl_xor(mx, 16)); mx = fmaxf(mx, __shfl_xor(mx, 32));
.LBB0_1079:
	v_readlane_b32 s16, v254, 55
	s_add_i32 s1, s15, -2
	v_readlane_b32 s18, v254, 57
	v_readlane_b32 s19, v254, 58
	v_cmp_le_i32_e32 vcc, s1, v107
	v_readlane_b32 s17, v254, 56
	v_lshl_add_u64 v[122:123], s[18:19], 0, v[112:113]
	s_and_saveexec_b64 s[12:13], vcc
	s_cbranch_execz .LBB0_1081
	v_add_co_u32_e32 v80, vcc, 0x1b900000, v122
	s_mov_b32 s16, 0xff800000
	v_addc_co_u32_e32 v81, vcc, 0, v123, vcc
	global_load_dwordx2 v[126:127], v[80:81], off
	v_add_co_u32_e32 v80, vcc, 0x1b902000, v122
	s_waitcnt vmcnt(0)
	v_lshrrev_b32_e32 v147, v132, v126
	v_addc_co_u32_e32 v81, vcc, 0, v123, vcc
	global_load_dwordx2 v[128:129], v[80:81], off
	ds_read_b128 v[80:83], v139
	ds_read_b128 v[84:87], v140
	s_waitcnt lgkmcnt(1)
	v_mfma_f32_16x16x32_f16 v[88:91], v[80:83], v[0:3], 0
	v_and_b32_e32 v130, 1, v147
	v_cmp_eq_u32_e32 vcc, 1, v130
	v_bfe_i32 v141, v147, 1, 1
	v_mfma_f32_16x16x32_f16 v[80:83], v[80:83], v[4:7], 0
	v_lshrrev_b32_e32 v126, v138, v126
	s_waitcnt lgkmcnt(0)
	v_mfma_f32_16x16x32_f16 v[142:145], v[84:87], v[8:11], v[88:91]
	v_mfma_f32_16x16x32_f16 v[154:157], v[84:87], v[12:15], v[80:83]
	s_nop 3
	ds_read_b128 v[80:83], v139 offset:2048
	ds_read_b128 v[84:87], v140 offset:2048
	s_waitcnt lgkmcnt(1)
	v_mfma_f32_16x16x32_f16 v[88:91], v[80:83], v[0:3], 0
	v_mfma_f32_16x16x32_f16 v[80:83], v[80:83], v[4:7], 0
	s_waitcnt lgkmcnt(0)
	v_mfma_f32_16x16x32_f16 v[100:103], v[84:87], v[8:11], v[88:91]
	v_mfma_f32_16x16x32_f16 v[96:99], v[84:87], v[12:15], v[80:83]
	s_nop 4
	ds_read_b128 v[80:83], v139 offset:4096
	ds_read_b128 v[88:91], v140 offset:4096
	s_waitcnt lgkmcnt(1)
	v_mfma_f32_16x16x32_f16 v[84:87], v[80:83], v[0:3], 0
	v_mfma_f32_16x16x32_f16 v[80:83], v[80:83], v[4:7], 0
	s_waitcnt lgkmcnt(0)
	v_mfma_f32_16x16x32_f16 v[84:87], v[88:91], v[8:11], v[84:87]
	v_mfma_f32_16x16x32_f16 v[80:83], v[88:91], v[12:15], v[80:83]
	ds_read_b128 v[88:91], v139 offset:6144
	ds_read_b128 v[92:95], v140 offset:6144
	s_waitcnt lgkmcnt(1)
	v_mfma_f32_16x16x32_f16 v[158:161], v[88:91], v[0:3], 0
	v_mfma_f32_16x16x32_f16 v[162:165], v[88:91], v[4:7], 0
	s_waitcnt lgkmcnt(0)
	v_mfma_f32_16x16x32_f16 v[88:91], v[92:95], v[8:11], v[158:161]
	s_nop 4
	v_cndmask_b32_e32 v159, v187, v142, vcc
	v_bfe_i32 v142, v147, 2, 1
	v_mfma_f32_16x16x32_f16 v[92:95], v[92:95], v[12:15], v[162:165]
	s_waitcnt vmcnt(0)
	v_lshrrev_b32_e32 v158, v132, v128
	v_and_b32_e32 v130, 1, v158
	v_cmp_eq_u32_e32 vcc, 1, v130
	v_lshrrev_b32_e32 v128, v138, v128
	s_nop 0
	v_cndmask_b32_e32 v130, v187, v154, vcc
	v_bfi_b32 v154, v141, v143, v187
	v_and_b32_e32 v141, 2, v158
	v_cmp_ne_u32_e32 vcc, 0, v141
	v_bfe_i32 v143, v147, 3, 1
	v_bfe_i32 v147, v126, 0, 1
	v_cndmask_b32_e32 v141, v187, v155, vcc
	v_bfi_b32 v144, v142, v144, v187
	v_and_b32_e32 v142, 4, v158
	v_cmp_ne_u32_e32 vcc, 0, v142
	s_nop 1
	v_cndmask_b32_e32 v142, v187, v156, vcc
	v_bfi_b32 v145, v143, v145, v187
	v_and_b32_e32 v143, 8, v158
	v_cmp_ne_u32_e32 vcc, 0, v143
	s_nop 1
	v_cndmask_b32_e32 v143, v187, v157, vcc
	v_bfi_b32 v100, v147, v100, v187
	v_and_b32_e32 v147, 1, v128
	v_cmp_eq_u32_e32 vcc, 1, v147
	s_nop 1
	v_cndmask_b32_e32 v147, v187, v96, vcc
	v_and_b32_e32 v96, 2, v126
	v_cmp_ne_u32_e32 vcc, 0, v96
	s_nop 1
	v_cndmask_b32_e32 v96, v187, v101, vcc
	v_bfe_i32 v101, v128, 1, 1
	v_bfi_b32 v97, v101, v97, v187
	v_and_b32_e32 v101, 4, v126
	v_cmp_ne_u32_e32 vcc, 0, v101
	s_nop 1
	v_cndmask_b32_e32 v101, v187, v102, vcc
	v_bfe_i32 v102, v128, 2, 1
	v_bfi_b32 v98, v102, v98, v187
	v_and_b32_e32 v102, 8, v126
	v_lshrrev_b32_e32 v126, v132, v129
	v_cmp_ne_u32_e32 vcc, 0, v102
	s_nop 1
	v_cndmask_b32_e32 v102, v187, v103, vcc
	v_and_b32_e32 v103, 8, v128
	v_cmp_ne_u32_e32 vcc, 0, v103
	s_nop 1
	v_cndmask_b32_e32 v103, v187, v99, vcc
	v_lshrrev_b32_e32 v99, v132, v127
	v_bfe_i32 v128, v99, 0, 1
	v_bfi_b32 v84, v128, v84, v187
	v_and_b32_e32 v128, 1, v126
	v_cmp_eq_u32_e32 vcc, 1, v128
	s_nop 1
	v_cndmask_b32_e32 v128, v187, v80, vcc
	v_and_b32_e32 v80, 2, v99
	v_cmp_ne_u32_e32 vcc, 0, v80
	s_nop 1
	v_cndmask_b32_e32 v80, v187, v85, vcc
	v_bfe_i32 v85, v126, 1, 1
	v_bfi_b32 v81, v85, v81, v187
	v_and_b32_e32 v85, 4, v99
	v_cmp_ne_u32_e32 vcc, 0, v85
	s_nop 1
	v_cndmask_b32_e32 v85, v187, v86, vcc
	v_bfe_i32 v86, v126, 2, 1
	v_bfi_b32 v155, v86, v82, v187
	v_bfe_i32 v86, v126, 3, 1
	v_and_b32_e32 v82, 8, v99
	v_cmp_ne_u32_e32 vcc, 0, v82
	s_nop 1
	v_cndmask_b32_e32 v82, v187, v87, vcc
	v_bfi_b32 v83, v86, v83, v187
	v_lshrrev_b32_e32 v86, v138, v127
	v_lshrrev_b32_e32 v87, v138, v129
	v_bfe_i32 v99, v86, 0, 1
	v_bfi_b32 v88, v99, v88, v187
	v_bfe_i32 v99, v87, 0, 1
	v_bfi_b32 v126, v99, v92, v187
	v_bfe_i32 v92, v86, 1, 1
	v_bfi_b32 v89, v92, v89, v187
	v_bfe_i32 v92, v87, 1, 1
	v_bfi_b32 v127, v92, v93, v187
	v_bfe_i32 v92, v86, 2, 1
	v_bfe_i32 v86, v86, 3, 1
	v_bfi_b32 v93, v92, v90, v187
	v_bfe_i32 v90, v87, 2, 1
	v_bfi_b32 v129, v90, v94, v187
	v_bfi_b32 v91, v86, v91, v187
	v_bfe_i32 v86, v87, 3, 1
	v_bfi_b32 v156, v86, v95, v187
	v_max_f32_e32 v86, v144, v145
	v_max_f32_e32 v87, v101, v102
	v_max_f32_e32 v90, v84, v80
	v_max_f32_e32 v92, v85, v82
	v_max_f32_e32 v94, v93, v91
	v_max3_f32 v94, v88, v89, v94
	v_max3_f32 v86, v159, v154, v86
	v_max3_f32 v87, v100, v96, v87
	v_max3_f32 v90, v90, v92, v94
	v_max3_f32 v86, v86, v87, v90
	ds_bpermute_b32 v87, v189, v86
	s_waitcnt lgkmcnt(0)
	v_max_f32_e32 v86, v86, v87
	ds_bpermute_b32 v87, v188, v86
	s_waitcnt lgkmcnt(0)
; DI float softmax_step(f32x4 (&st)[4], float& m, float& lsum) {
;   float mx = fmaxf(fmaxf(fmaxf(st[0][0], st[0][1]), fmaxf(st[0][2], st[0][3])), fmaxf(fmaxf(st[1][0], st[1][1]), fmaxf(st[1][2], st[1][3])));
;   mx = fmaxf(mx, fmaxf(fmaxf(fmaxf(st[2][0], st[2][1]), fmaxf(st[2][2], st[2][3])), fmaxf(fmaxf(st[3][0], st[3][1]), fmaxf(st[3][2], st[3][3]))));
;   mx = fmaxf(mx, __shfl_xor(mx, 16)); mx = fmaxf(mx, __shfl_xor(mx, 32));
;   const float mn = fmaxf(m, mx);
;   const float mu = mn == -INFINITY ? 0.f : mn;
;   const float alpha = __builtin_amdgcn_exp2f(m - mu);
;   float ps = 0.f;
; #pragma unroll
;   for (int kt = 0; kt < 4; ++kt)
; #pragma unroll
;     for (int j = 0; j < 4; ++j) { const float p = __builtin_amdgcn_exp2f(st[kt][j] - mu); st[kt][j] = p; ps += p; }
;   lsum = lsum * alpha + ps; m = mn;
;   return alpha;
; }
	v_max3_f32 v99, v131, v86, v87
	v_cmp_neq_f32_e32 vcc, s16, v99
	s_nop 1
	v_cndmask_b32_e32 v87, 0, v99, vcc
	v_sub_f32_e32 v86, v159, v87
	v_exp_f32_e32 v162, v86
	v_sub_f32_e32 v86, v154, v87
	v_exp_f32_e32 v164, v86
	v_sub_f32_e32 v86, v144, v87
	v_exp_f32_e32 v166, v86
	v_sub_f32_e32 v86, v145, v87
	v_sub_f32_e32 v80, v80, v87
	v_exp_f32_e32 v168, v86
	v_sub_f32_e32 v86, v100, v87
	v_exp_f32_e32 v94, v80
	v_sub_f32_e32 v80, v85, v87
	v_exp_f32_e32 v170, v86
	v_sub_f32_e32 v86, v96, v87
	v_exp_f32_e32 v92, v80
	v_sub_f32_e32 v80, v82, v87
	v_exp_f32_e32 v190, v86
	v_sub_f32_e32 v86, v101, v87
	v_exp_f32_e32 v90, v80
	v_sub_f32_e32 v80, v88, v87
	v_exp_f32_e32 v192, v86
	v_sub_f32_e32 v86, v102, v87
	v_exp_f32_e32 v88, v80
	v_sub_f32_e32 v80, v89, v87
	v_exp_f32_e32 v194, v86
	v_sub_f32_e32 v84, v84, v87
	v_exp_f32_e32 v86, v80
	v_sub_f32_e32 v80, v93, v87
	v_exp_f32_e32 v96, v84
	v_exp_f32_e32 v82, v80
	v_sub_f32_e32 v80, v91, v87
	v_sub_f32_e32 v84, v131, v87
	v_max_f32_e32 v85, v142, v143
	v_max_f32_e32 v87, v98, v103
	v_max_f32_e32 v89, v128, v81
	v_max_f32_e32 v91, v155, v83
	v_max_f32_e32 v93, v129, v156
	v_max3_f32 v93, v126, v127, v93
	v_max3_f32 v85, v130, v141, v85
	v_max3_f32 v87, v147, v97, v87
	v_max3_f32 v89, v89, v91, v93
	v_max3_f32 v85, v85, v87, v89
	ds_bpermute_b32 v87, v189, v85
	v_exp_f32_e32 v84, v84
	v_exp_f32_e32 v80, v80
	v_mov_b32_e32 v131, v99
	s_waitcnt lgkmcnt(0)
	v_max_f32_e32 v85, v85, v87
	ds_bpermute_b32 v87, v188, v85
	s_waitcnt lgkmcnt(0)
	v_max3_f32 v102, v146, v85, v87
	v_cmp_neq_f32_e32 vcc, s16, v102
	s_nop 1
	v_cndmask_b32_e32 v85, 0, v102, vcc
	v_sub_f32_e32 v87, v130, v85
	v_exp_f32_e32 v163, v87
	v_sub_f32_e32 v87, v141, v85
	v_exp_f32_e32 v165, v87
	v_sub_f32_e32 v87, v142, v85
	v_exp_f32_e32 v167, v87
	v_sub_f32_e32 v87, v143, v85
	v_exp_f32_e32 v169, v87
	v_sub_f32_e32 v87, v147, v85
	v_sub_f32_e32 v81, v81, v85
	v_exp_f32_e32 v171, v87
	v_sub_f32_e32 v87, v97, v85
	v_exp_f32_e32 v95, v81
	v_sub_f32_e32 v81, v155, v85
	v_exp_f32_e32 v191, v87
	v_sub_f32_e32 v87, v98, v85
	v_exp_f32_e32 v93, v81
	v_sub_f32_e32 v81, v83, v85
	v_exp_f32_e32 v193, v87
	v_sub_f32_e32 v87, v103, v85
	v_exp_f32_e32 v91, v81
	v_sub_f32_e32 v81, v126, v85
	v_exp_f32_e32 v195, v87
	v_sub_f32_e32 v87, v128, v85
	v_exp_f32_e32 v89, v81
	v_sub_f32_e32 v81, v127, v85
	v_exp_f32_e32 v97, v87
	v_exp_f32_e32 v87, v81
	v_sub_f32_e32 v81, v129, v85
	v_exp_f32_e32 v83, v81
	v_sub_f32_e32 v81, v156, v85
	v_sub_f32_e32 v85, v146, v85
	v_exp_f32_e32 v98, v85
	v_pk_mul_f32 v[156:157], v[70:71], v[84:85] op_sel_hi:[1,0]
	v_pk_mul_f32 v[154:155], v[68:69], v[84:85] op_sel_hi:[1,0]
	v_pk_mul_f32 v[128:129], v[62:63], v[84:85] op_sel_hi:[1,0]
	v_pk_mul_f32 v[142:143], v[56:57], v[98:99] op_sel_hi:[1,0]
	v_pk_mul_f32 v[70:71], v[50:51], v[98:99] op_sel_hi:[1,0]
	v_pk_mul_f32 v[68:69], v[48:49], v[98:99] op_sel_hi:[1,0]
	v_pk_mul_f32 v[50:51], v[74:75], v[84:85] op_sel_hi:[1,0]
	v_pk_mul_f32 v[48:49], v[72:73], v[84:85] op_sel_hi:[1,0]
	v_pk_add_f32 v[56:57], v[162:163], 0 op_sel_hi:[1,0]
	ds_read_b128 v[72:75], v139 offset:9216
	v_pk_add_f32 v[56:57], v[164:165], v[56:57]
	v_pk_mul_f32 v[126:127], v[60:61], v[84:85] op_sel_hi:[1,0]
	v_pk_add_f32 v[56:57], v[166:167], v[56:57]
	v_pk_mul_f32 v[144:145], v[58:59], v[98:99] op_sel_hi:[1,0]
	v_pk_add_f32 v[56:57], v[168:169], v[56:57]
	v_cvt_pk_f16_f32 v58, v170, v190
	v_pk_add_f32 v[56:57], v[170:171], v[56:57]
	v_cvt_pk_f16_f32 v59, v192, v194
	v_pk_add_f32 v[56:57], v[190:191], v[56:57]
	v_pk_mul_f32 v[160:161], v[66:67], v[98:99] op_sel_hi:[1,0]
	v_pk_add_f32 v[56:57], v[192:193], v[56:57]
	v_pk_mul_f32 v[158:159], v[64:65], v[98:99] op_sel_hi:[1,0]
	v_pk_add_f32 v[56:57], v[194:195], v[56:57]
	v_pk_mul_f32 v[66:67], v[54:55], v[84:85] op_sel_hi:[1,0]
	v_pk_add_f32 v[100:101], v[96:97], v[56:57]
	v_cvt_pk_f16_f32 v56, v162, v164
	v_cvt_pk_f16_f32 v57, v166, v168
	v_pk_mul_f32 v[64:65], v[52:53], v[84:85] op_sel_hi:[1,0]
	v_pk_mul_f32 v[54:55], v[78:79], v[98:99] op_sel_hi:[1,0]
	v_pk_mul_f32 v[52:53], v[76:77], v[98:99] op_sel_hi:[1,0]
	s_waitcnt lgkmcnt(0)
	v_mfma_f32_16x16x32_f16 v[76:79], v[72:75], v[56:59], v[126:129]
	v_cvt_pk_f16_f32 v60, v163, v165
	v_cvt_pk_f16_f32 v61, v167, v169
	v_cvt_pk_f16_f32 v62, v171, v191
	ds_read_b128 v[126:129], v139 offset:11264
	v_cvt_pk_f16_f32 v63, v193, v195
	v_exp_f32_e32 v81, v81
	v_cvt_pk_f16_f32 v190, v96, v94
	v_mfma_f32_16x16x32_f16 v[72:75], v[72:75], v[60:63], v[142:145]
	v_cvt_pk_f16_f32 v191, v92, v90
	v_cvt_pk_f16_f32 v192, v88, v86
	v_cvt_pk_f16_f32 v193, v82, v80
	s_waitcnt lgkmcnt(0)
	v_mfma_f32_16x16x32_f16 v[142:145], v[126:129], v[56:59], v[154:157]
	v_cvt_pk_f16_f32 v194, v97, v95
	v_cvt_pk_f16_f32 v195, v93, v91
	s_nop 0
	ds_read_b128 v[154:157], v139 offset:13312
	v_mfma_f32_16x16x32_f16 v[126:129], v[126:129], v[60:63], v[158:161]
	v_cvt_pk_f16_f32 v196, v89, v87
	v_cvt_pk_f16_f32 v197, v83, v81
	v_pk_add_f32 v[94:95], v[94:95], v[100:101]
	s_waitcnt lgkmcnt(0)
	v_mfma_f32_16x16x32_f16 v[158:161], v[154:157], v[56:59], v[64:67]
	s_nop 2
	ds_read_b128 v[64:67], v139 offset:15360
	v_pk_add_f32 v[92:93], v[92:93], v[94:95]
	v_mov_b32_e32 v85, v98
	s_waitcnt lgkmcnt(0)
	v_mfma_f32_16x16x32_f16 v[162:165], v[64:67], v[56:59], v[48:51]
	s_nop 2
	ds_read_b128 v[48:51], v140 offset:9216
	v_pk_add_f32 v[90:91], v[90:91], v[92:93]
	v_mov_b32_e32 v146, v102
	v_mfma_f32_16x16x32_f16 v[154:157], v[154:157], v[60:63], v[68:71]
	v_add_f32_e64 v88, v88, v90
	v_add_f32_e64 v89, v89, v91
	v_pk_add_f32 v[86:87], v[86:87], v[88:89]
	v_mfma_f32_16x16x32_f16 v[166:169], v[64:67], v[60:63], v[52:55]
	v_add_f32_e64 v82, v82, v86
	v_add_f32_e64 v83, v83, v87
	v_pk_add_f32 v[80:81], v[80:81], v[82:83]
	s_waitcnt lgkmcnt(0)
	v_mfma_f32_16x16x32_f16 v[60:63], v[48:51], v[190:193], v[76:79]
	v_fma_f32 v118, v118, v84, v80
	v_fma_f32 v119, v119, v85, v81
	v_mfma_f32_16x16x32_f16 v[56:59], v[48:51], v[194:197], v[72:75]
	ds_read_b128 v[48:51], v140 offset:11264
	ds_read_b128 v[76:79], v140 offset:15360
	s_waitcnt lgkmcnt(1)
	v_mfma_f32_16x16x32_f16 v[68:71], v[48:51], v[190:193], v[142:145]
	v_mfma_f32_16x16x32_f16 v[64:67], v[48:51], v[194:197], v[126:129]
	ds_read_b128 v[48:51], v140 offset:13312
	s_waitcnt lgkmcnt(0)
	v_mfma_f32_16x16x32_f16 v[52:55], v[48:51], v[190:193], v[158:161]
	v_mfma_f32_16x16x32_f16 v[48:51], v[48:51], v[194:197], v[154:157]
	v_mfma_f32_16x16x32_f16 v[72:75], v[76:79], v[190:193], v[162:165]
	v_mfma_f32_16x16x32_f16 v[76:79], v[76:79], v[194:197], v[166:169]

; #define MFMA16(a, b, c) __builtin_amdgcn_mfma_f32_16x16x32_f16((a), (b), (c), 0, 0, 0)
; DI void qk_tile2(f32x4 (&sa)[4], f32x4 (&sb)[4], const char* sK, const bf16x8 (&qa)[2], const bf16x8 (&qb)[2], int lr, int g) {
; #pragma unroll
;   for (int kt = 0; kt < 4; ++kt) {
;     const bf16x8 k0 = *(const bf16x8*)(sK + (kt * 16 + lr) * 128 + ((g ^ ((lr >> 1) & 7)) << 4)), k1 = *(const bf16x8*)(sK + (kt * 16 + lr) * 128 + (((4 + g) ^ ((lr >> 1) & 7)) << 4));
;     sa[kt] = MFMA16(k0, qa[0], ((f32x4){0.f, 0.f, 0.f, 0.f})); sb[kt] = MFMA16(k0, qb[0], ((f32x4){0.f, 0.f, 0.f, 0.f}));
;     sa[kt] = MFMA16(k1, qa[1], sa[kt]); sb[kt] = MFMA16(k1, qb[1], sb[kt]);
;   }
; }
; DI float softmax_step(f32x4 (&st)[4], float& m, float& lsum) {
;   float mx = fmaxf(fmaxf(fmaxf(st[0][0], st[0][1]), fmaxf(st[0][2], st[0][3])), fmaxf(fmaxf(st[1][0], st[1][1]), fmaxf(st[1][2], st[1][3])));
;   mx = fmaxf(mx, fmaxf(fmaxf(fmaxf(st[2][0], st[2][1]), fmaxf(st[2][2], st[2][3])), fmaxf(fmaxf(st[3][0], st[3][1]), fmaxf(st[3][2], st[3][3]))));
;   mx = fmaxf(mx, __shfl_xor(mx, 16)); mx = fmaxf(mx, __shfl_xor(mx, 32));
;   const float mn = fmaxf(m, mx);
;   const float mu = mn == -INFINITY ? 0.f : mn;
;   const float alpha = __builtin_amdgcn_exp2f(m - mu);
;   float ps = 0.f;
; #pragma unroll
;   for (int kt = 0; kt < 4; ++kt)
; #pragma unroll
;     for (int j = 0; j < 4; ++j) { const float p = __builtin_amdgcn_exp2f(st[kt][j] - mu); st[kt][j] = p; ps += p; }
;   lsum = lsum * alpha + ps; m = mn;
;   return alpha;
; }
.LBB0_1085:
	v_add_co_u32_e32 v80, vcc, 0x1b900000, v122
	s_mov_b32 s1, 0xff800000
	v_addc_co_u32_e32 v81, vcc, 0, v123, vcc
	global_load_dwordx2 v[128:129], v[80:81], off offset:8
	v_add_co_u32_e32 v80, vcc, 0x1b902000, v122
	v_addc_co_u32_e32 v81, vcc, 0, v123, vcc
	global_load_dwordx2 v[144:145], v[80:81], off offset:8
	ds_read_b128 v[80:83], v139 offset:18432
	ds_read_b128 v[84:87], v140 offset:18432
	s_waitcnt lgkmcnt(1)
	v_mfma_f32_16x16x32_f16 v[88:91], v[80:83], v[0:3], 0
	v_mfma_f32_16x16x32_f16 v[80:83], v[80:83], v[4:7], 0
	s_waitcnt lgkmcnt(0)
	v_mfma_f32_16x16x32_f16 v[88:91], v[84:87], v[8:11], v[88:91]
	v_mfma_f32_16x16x32_f16 v[80:83], v[84:87], v[12:15], v[80:83]
	ds_read_b128 v[84:87], v139 offset:20480
	ds_read_b128 v[92:95], v140 offset:20480
	s_waitcnt lgkmcnt(1)
	v_mfma_f32_16x16x32_f16 v[96:99], v[84:87], v[0:3], 0
	v_mfma_f32_16x16x32_f16 v[84:87], v[84:87], v[4:7], 0
	s_waitcnt lgkmcnt(0)
	v_mfma_f32_16x16x32_f16 v[96:99], v[92:95], v[8:11], v[96:99]
	v_mfma_f32_16x16x32_f16 v[84:87], v[92:95], v[12:15], v[84:87]
	ds_read_b128 v[92:95], v139 offset:22528
	ds_read_b128 v[100:103], v140 offset:22528
	s_waitcnt lgkmcnt(1)
	v_mfma_f32_16x16x32_f16 v[120:123], v[92:95], v[0:3], 0
	v_mfma_f32_16x16x32_f16 v[92:95], v[92:95], v[4:7], 0
	s_waitcnt lgkmcnt(0)
	v_mfma_f32_16x16x32_f16 v[120:123], v[100:103], v[8:11], v[120:123]
	v_mfma_f32_16x16x32_f16 v[92:95], v[100:103], v[12:15], v[92:95]
	ds_read_b128 v[100:103], v139 offset:24576
	ds_read_b128 v[124:127], v140 offset:24576
	s_waitcnt lgkmcnt(1)
	v_mfma_f32_16x16x32_f16 v[154:157], v[100:103], v[0:3], 0
	v_mfma_f32_16x16x32_f16 v[100:103], v[100:103], v[4:7], 0
	s_waitcnt lgkmcnt(0)
	v_mfma_f32_16x16x32_f16 v[154:157], v[124:127], v[8:11], v[154:157]
	v_mfma_f32_16x16x32_f16 v[100:103], v[124:127], v[12:15], v[100:103]
	s_waitcnt vmcnt(1)
	v_lshrrev_b32_e32 v124, v132, v128
	v_bfe_i32 v126, v124, 0, 1
	v_bfi_b32 v88, v126, v88, v187
	s_waitcnt vmcnt(0)
	v_lshrrev_b32_e32 v125, v132, v144
	v_bfe_i32 v126, v125, 0, 1
	v_bfi_b32 v80, v126, v80, v187
	v_bfe_i32 v126, v124, 1, 1
	v_bfi_b32 v89, v126, v89, v187
	v_bfe_i32 v126, v125, 1, 1
	v_bfi_b32 v81, v126, v81, v187
	v_bfe_i32 v126, v124, 2, 1
	v_bfe_i32 v124, v124, 3, 1
	v_bfi_b32 v90, v126, v90, v187
	v_bfe_i32 v126, v125, 2, 1
	v_bfi_b32 v82, v126, v82, v187
	v_bfi_b32 v91, v124, v91, v187
	v_bfe_i32 v124, v125, 3, 1
	v_lshrrev_b32_e32 v125, v138, v144
	v_bfi_b32 v83, v124, v83, v187
	v_lshrrev_b32_e32 v124, v138, v128
	v_bfe_i32 v126, v124, 0, 1
	v_bfi_b32 v96, v126, v96, v187
	v_bfe_i32 v126, v125, 0, 1
	v_bfi_b32 v127, v126, v84, v187
	v_bfe_i32 v84, v124, 1, 1
	v_bfi_b32 v97, v84, v97, v187
	v_bfe_i32 v84, v125, 1, 1
	v_bfi_b32 v147, v84, v85, v187
	v_bfe_i32 v84, v124, 2, 1
	v_bfi_b32 v85, v84, v98, v187
	v_bfe_i32 v84, v125, 2, 1
	v_bfi_b32 v98, v84, v86, v187
	v_bfe_i32 v84, v124, 3, 1
	v_bfi_b32 v99, v84, v99, v187
	v_bfe_i32 v84, v125, 3, 1
	v_lshrrev_b32_e32 v86, v132, v145
	v_bfi_b32 v125, v84, v87, v187
	v_lshrrev_b32_e32 v84, v132, v129
	v_and_b32_e32 v87, 1, v84
	v_cmp_eq_u32_e32 vcc, 1, v87
	s_nop 1
	v_cndmask_b32_e32 v87, v187, v120, vcc
	v_bfe_i32 v120, v86, 0, 1
	v_bfi_b32 v92, v120, v92, v187
	v_and_b32_e32 v120, 2, v84
	v_cmp_ne_u32_e32 vcc, 0, v120
	s_nop 1
	v_cndmask_b32_e32 v120, v187, v121, vcc
	v_bfe_i32 v121, v86, 1, 1
	v_bfi_b32 v93, v121, v93, v187
	v_and_b32_e32 v121, 4, v84
	v_bfe_i32 v84, v84, 3, 1
	v_cmp_ne_u32_e32 vcc, 0, v121
	s_nop 1
	v_cndmask_b32_e32 v121, v187, v122, vcc
	v_bfe_i32 v122, v86, 2, 1
	v_bfi_b32 v94, v122, v94, v187
	v_bfi_b32 v122, v84, v123, v187
	v_bfe_i32 v84, v86, 3, 1
	v_lshrrev_b32_e32 v86, v138, v145
	v_bfi_b32 v95, v84, v95, v187
	v_lshrrev_b32_e32 v84, v138, v129
	v_and_b32_e32 v123, 1, v84
	v_cmp_eq_u32_e32 vcc, 1, v123
	v_bfe_i32 v124, v86, 0, 1
	s_nop 0
	v_cndmask_b32_e32 v123, v187, v154, vcc
	v_bfi_b32 v129, v124, v100, v187
	v_bfe_i32 v124, v86, 1, 1
	v_and_b32_e32 v100, 2, v84
	v_cmp_ne_u32_e32 vcc, 0, v100
	s_nop 1
	v_cndmask_b32_e32 v100, v187, v155, vcc
	v_bfi_b32 v101, v124, v101, v187
	v_bfe_i32 v124, v84, 2, 1
	v_bfe_i32 v84, v84, 3, 1
	v_bfi_b32 v128, v124, v156, v187
	v_bfe_i32 v124, v86, 2, 1
	v_bfi_b32 v102, v124, v102, v187
	v_bfi_b32 v130, v84, v157, v187
	v_bfe_i32 v84, v86, 3, 1
	v_bfi_b32 v103, v84, v103, v187
	v_max_f32_e32 v84, v90, v91
	v_max_f32_e32 v86, v85, v99
	v_max_f32_e32 v124, v87, v120
	v_max_f32_e32 v126, v121, v122
	v_max_f32_e32 v144, v128, v130
	v_max3_f32 v144, v123, v100, v144
	v_max3_f32 v84, v88, v89, v84
	v_max3_f32 v86, v96, v97, v86
	v_max3_f32 v124, v124, v126, v144
	v_max3_f32 v84, v84, v86, v124
	ds_bpermute_b32 v86, v189, v84
	s_waitcnt lgkmcnt(0)
	v_max_f32_e32 v84, v84, v86
	ds_bpermute_b32 v86, v188, v84
	s_waitcnt lgkmcnt(0)
	v_max3_f32 v144, v131, v84, v86
	v_cmp_neq_f32_e32 vcc, s1, v144
	s_nop 1
	v_cndmask_b32_e32 v145, 0, v144, vcc
	v_sub_f32_e32 v84, v88, v145
	v_sub_f32_e32 v88, v90, v145
	v_exp_f32_e32 v162, v88
	v_sub_f32_e32 v88, v91, v145
	v_sub_f32_e32 v85, v85, v145
	v_exp_f32_e32 v164, v88
	v_sub_f32_e32 v88, v96, v145
	v_exp_f32_e32 v170, v85
	v_sub_f32_e32 v85, v99, v145
	v_exp_f32_e32 v166, v88
	v_sub_f32_e32 v88, v97, v145
	v_exp_f32_e32 v190, v85
	v_sub_f32_e32 v85, v87, v145
	v_exp_f32_e32 v168, v88
	v_exp_f32_e32 v88, v85
	v_sub_f32_e32 v85, v120, v145
	v_exp_f32_e32 v90, v85
	v_sub_f32_e32 v85, v121, v145
	v_exp_f32_e32 v120, v85
	v_sub_f32_e32 v85, v122, v145
	v_exp_f32_e32 v122, v85
	v_sub_f32_e32 v85, v123, v145
	v_exp_f32_e32 v124, v85
	v_sub_f32_e32 v85, v100, v145
	v_exp_f32_e32 v126, v85
	v_sub_f32_e32 v85, v128, v145
	v_exp_f32_e32 v128, v85
	v_sub_f32_e32 v85, v130, v145
	v_exp_f32_e32 v130, v85
	v_sub_f32_e32 v85, v131, v145
	v_exp_f32_e32 v100, v85
	v_sub_f32_e32 v86, v89, v145
	v_max_f32_e32 v85, v82, v83
	v_max_f32_e32 v87, v98, v125
	v_max_f32_e32 v89, v92, v93
	v_max_f32_e32 v91, v94, v95
	v_max_f32_e32 v96, v102, v103
	v_max3_f32 v96, v129, v101, v96
	v_max3_f32 v85, v80, v81, v85
	v_max3_f32 v87, v127, v147, v87
	v_max3_f32 v89, v89, v91, v96
	v_max3_f32 v85, v85, v87, v89
	ds_bpermute_b32 v87, v189, v85
	v_exp_f32_e32 v84, v84
	v_exp_f32_e32 v86, v86
	v_pk_mul_f32 v[70:71], v[70:71], v[100:101] op_sel_hi:[1,0]
	v_pk_mul_f32 v[68:69], v[68:69], v[100:101] op_sel_hi:[1,0]
	s_waitcnt lgkmcnt(0)
; DI float softmax_step(f32x4 (&st)[4], float& m, float& lsum) {
;   float mx = fmaxf(fmaxf(fmaxf(st[0][0], st[0][1]), fmaxf(st[0][2], st[0][3])), fmaxf(fmaxf(st[1][0], st[1][1]), fmaxf(st[1][2], st[1][3])));
;   mx = fmaxf(mx, fmaxf(fmaxf(fmaxf(st[2][0], st[2][1]), fmaxf(st[2][2], st[2][3])), fmaxf(fmaxf(st[3][0], st[3][1]), fmaxf(st[3][2], st[3][3]))));
;   mx = fmaxf(mx, __shfl_xor(mx, 16)); mx = fmaxf(mx, __shfl_xor(mx, 32));
;   const float mn = fmaxf(m, mx);
;   const float mu = mn == -INFINITY ? 0.f : mn;
;   const float alpha = __builtin_amdgcn_exp2f(m - mu);
;   float ps = 0.f;
; #pragma unroll
;   for (int kt = 0; kt < 4; ++kt)
; #pragma unroll
;     for (int j = 0; j < 4; ++j) { const float p = __builtin_amdgcn_exp2f(st[kt][j] - mu); st[kt][j] = p; ps += p; }
;   lsum = lsum * alpha + ps; m = mn;
;   return alpha;
; }
	v_max_f32_e32 v85, v85, v87
	ds_bpermute_b32 v87, v188, v85
	v_pk_mul_f32 v[156:157], v[54:55], v[100:101] op_sel_hi:[1,0]
	v_pk_mul_f32 v[154:155], v[52:53], v[100:101] op_sel_hi:[1,0]
	s_waitcnt lgkmcnt(0)
	v_max3_f32 v145, v146, v85, v87
	v_cmp_neq_f32_e32 vcc, s1, v145
	s_nop 1
	v_cndmask_b32_e32 v96, 0, v145, vcc
	v_sub_f32_e32 v80, v80, v96
	v_exp_f32_e32 v85, v80
	v_sub_f32_e32 v80, v81, v96
	v_exp_f32_e32 v87, v80
	v_sub_f32_e32 v80, v82, v96
	v_exp_f32_e32 v163, v80
	v_sub_f32_e32 v80, v83, v96
	v_exp_f32_e32 v165, v80
	v_sub_f32_e32 v80, v127, v96
	v_exp_f32_e32 v167, v80
	v_sub_f32_e32 v80, v147, v96
	v_exp_f32_e32 v169, v80
	v_sub_f32_e32 v80, v98, v96
	v_exp_f32_e32 v171, v80
	v_sub_f32_e32 v80, v125, v96
	v_exp_f32_e32 v191, v80
	v_sub_f32_e32 v80, v92, v96
	v_exp_f32_e32 v89, v80
	v_sub_f32_e32 v80, v93, v96
	v_exp_f32_e32 v91, v80
	v_sub_f32_e32 v80, v94, v96
	v_exp_f32_e32 v121, v80
	v_sub_f32_e32 v80, v95, v96
	v_exp_f32_e32 v123, v80
	v_sub_f32_e32 v80, v129, v96
	v_exp_f32_e32 v125, v80
	v_sub_f32_e32 v80, v101, v96
	v_exp_f32_e32 v127, v80
	v_sub_f32_e32 v80, v102, v96
	v_exp_f32_e32 v129, v80
	v_sub_f32_e32 v80, v103, v96
	v_exp_f32_e32 v131, v80
	v_sub_f32_e32 v80, v146, v96
	v_exp_f32_e32 v102, v80
	v_pk_mul_f32 v[82:83], v[62:63], v[100:101] op_sel_hi:[1,0]
	v_pk_mul_f32 v[80:81], v[60:61], v[100:101] op_sel_hi:[1,0]
	v_cvt_pk_f16_f32 v60, v84, v86
	v_pk_mul_f32 v[160:161], v[50:51], v[102:103] op_sel_hi:[1,0]
	v_pk_mul_f32 v[158:159], v[48:49], v[102:103] op_sel_hi:[1,0]
	v_pk_mul_f32 v[50:51], v[74:75], v[100:101] op_sel_hi:[1,0]
	v_pk_mul_f32 v[48:49], v[72:73], v[100:101] op_sel_hi:[1,0]
	ds_read_b128 v[72:75], v139 offset:29696
	v_pk_mul_f32 v[92:93], v[56:57], v[102:103] op_sel_hi:[1,0]
	v_pk_add_f32 v[56:57], v[84:85], 0 op_sel_hi:[1,0]
	v_pk_mul_f32 v[98:99], v[66:67], v[102:103] op_sel_hi:[1,0]
	v_pk_add_f32 v[56:57], v[86:87], v[56:57]
	v_pk_mul_f32 v[96:97], v[64:65], v[102:103] op_sel_hi:[1,0]
	v_pk_add_f32 v[56:57], v[162:163], v[56:57]
	v_cvt_pk_f16_f32 v61, v162, v164
	v_pk_add_f32 v[56:57], v[164:165], v[56:57]
	v_cvt_pk_f16_f32 v62, v166, v168
	v_pk_add_f32 v[56:57], v[166:167], v[56:57]
	v_cvt_pk_f16_f32 v63, v170, v190
	v_pk_add_f32 v[56:57], v[168:169], v[56:57]
	v_cvt_pk_f16_f32 v84, v85, v87
	v_pk_add_f32 v[56:57], v[170:171], v[56:57]
	v_cvt_pk_f16_f32 v85, v163, v165
	v_cvt_pk_f16_f32 v86, v167, v169
	v_cvt_pk_f16_f32 v87, v171, v191
	ds_read_b128 v[64:67], v139 offset:27648
	v_pk_add_f32 v[56:57], v[190:191], v[56:57]
	s_waitcnt lgkmcnt(1)
	v_mfma_f32_16x16x32_f16 v[68:71], v[72:75], v[60:63], v[68:71]
	v_add_f32_e64 v56, v88, v56
	v_add_f32_e64 v57, v89, v57
	v_pk_mul_f32 v[94:95], v[58:59], v[102:103] op_sel_hi:[1,0]
	v_pk_add_f32 v[56:57], v[90:91], v[56:57]
	v_mfma_f32_16x16x32_f16 v[72:75], v[72:75], v[84:87], v[96:99]
	v_add_f32_e64 v56, v120, v56
	v_add_f32_e64 v57, v121, v57
	v_pk_mul_f32 v[54:55], v[78:79], v[102:103] op_sel_hi:[1,0]
	v_pk_add_f32 v[56:57], v[122:123], v[56:57]
	ds_read_b128 v[96:99], v139 offset:33792
	v_pk_add_f32 v[56:57], v[124:125], v[56:57]
	v_pk_mul_f32 v[52:53], v[76:77], v[102:103] op_sel_hi:[1,0]
	v_pk_add_f32 v[56:57], v[126:127], v[56:57]
	v_mov_b32_e32 v101, v102
	v_pk_add_f32 v[56:57], v[128:129], v[56:57]
	v_mov_b32_e32 v146, v145
	v_pk_add_f32 v[102:103], v[130:131], v[56:57]
	s_waitcnt lgkmcnt(1)
	v_mfma_f32_16x16x32_f16 v[56:59], v[64:67], v[60:63], v[80:83]
	v_fma_f32 v118, v118, v100, v102
	v_fma_f32 v119, v119, v101, v103
	s_nop 0
	ds_read_b128 v[80:83], v139 offset:31744
	v_mfma_f32_16x16x32_f16 v[64:67], v[64:67], v[84:87], v[92:95]
	s_waitcnt lgkmcnt(1)
	v_mfma_f32_16x16x32_f16 v[92:95], v[96:99], v[60:63], v[48:51]
	s_nop 2
	ds_read_b128 v[48:51], v140 offset:27648
	s_waitcnt lgkmcnt(1)
	v_mfma_f32_16x16x32_f16 v[76:79], v[80:83], v[60:63], v[154:157]
	v_mfma_f32_16x16x32_f16 v[80:83], v[80:83], v[84:87], v[158:161]
	v_mfma_f32_16x16x32_f16 v[84:87], v[96:99], v[84:87], v[52:55]
	v_cvt_pk_f16_f32 v96, v88, v90
	v_cvt_pk_f16_f32 v97, v120, v122
	v_cvt_pk_f16_f32 v98, v124, v126
	v_cvt_pk_f16_f32 v99, v128, v130
	v_cvt_pk_f16_f32 v88, v89, v91
	v_cvt_pk_f16_f32 v89, v121, v123
	v_cvt_pk_f16_f32 v90, v125, v127
	v_cvt_pk_f16_f32 v91, v129, v131
	s_waitcnt lgkmcnt(0)
	v_mfma_f32_16x16x32_f16 v[60:63], v[48:51], v[96:99], v[56:59]
	v_mov_b32_e32 v131, v144
	v_mfma_f32_16x16x32_f16 v[56:59], v[48:51], v[88:91], v[64:67]
	ds_read_b128 v[48:51], v140 offset:29696
	s_waitcnt lgkmcnt(0)
	v_mfma_f32_16x16x32_f16 v[68:71], v[48:51], v[96:99], v[68:71]
	v_mfma_f32_16x16x32_f16 v[64:67], v[48:51], v[88:91], v[72:75]
	ds_read_b128 v[48:51], v140 offset:31744
	s_waitcnt lgkmcnt(0)
	v_mfma_f32_16x16x32_f16 v[52:55], v[48:51], v[96:99], v[76:79]
	s_nop 2
	ds_read_b128 v[76:79], v140 offset:33792
	v_mfma_f32_16x16x32_f16 v[48:51], v[48:51], v[88:91], v[80:83]
	s_waitcnt lgkmcnt(0)
	v_mfma_f32_16x16x32_f16 v[72:75], v[76:79], v[96:99], v[92:95]
	v_mfma_f32_16x16x32_f16 v[76:79], v[76:79], v[88:91], v[84:87]
	s_or_b64 exec, exec, s[12:13]
	s_andn2_b64 vcc, exec, s[10:11]
	s_cbranch_vccnz .LBB0_1076
